# UP epilogue hand-written: per-row factors folded (rstd^2, -log2e*rstd), 5 VALU+2 trans per element instead of ~9, global stores in saddr form
# speedup vs baseline: 1.0189x; 1.0041x over previous
.LBB0_568:
	s_waitcnt vmcnt(0)
	v_add_f32_e32 v208, v168, v169
	v_add_f32_e32 v186, v170, v171
	v_add_f32_e32 v209, v150, v151
	v_add_f32_e32 v187, v152, v153
	v_add_f32_e32 v210, v156, v157
	v_add_f32_e32 v188, v158, v159
	v_add_f32_e32 v211, v160, v161
	v_add_f32_e32 v189, v162, v163
	v_add_f32_e32 v212, v164, v165
	v_add_f32_e32 v190, v166, v167
	v_add_f32_e32 v213, v172, v173
	v_add_f32_e32 v191, v174, v175
	v_add_f32_e32 v214, v176, v177
	v_add_f32_e32 v192, v178, v179
	v_add_f32_e32 v215, v180, v181
	v_add_f32_e32 v193, v182, v183
	v_add_f32_e32 v208, v208, v186
	v_add_f32_e32 v209, v209, v187
	v_add_f32_e32 v210, v210, v188
	v_add_f32_e32 v211, v211, v189
	v_add_f32_e32 v212, v212, v190
	v_add_f32_e32 v213, v213, v191
	v_add_f32_e32 v214, v214, v192
	v_add_f32_e32 v215, v215, v193
	v_fmamk_f32 v208, v208, 0x3a800000, v222
	v_fmamk_f32 v209, v209, 0x3a800000, v222
	v_fmamk_f32 v210, v210, 0x3a800000, v222
	v_fmamk_f32 v211, v211, 0x3a800000, v222
	v_fmamk_f32 v212, v212, 0x3a800000, v222
	v_fmamk_f32 v213, v213, 0x3a800000, v222
	v_fmamk_f32 v214, v214, 0x3a800000, v222
	v_fmamk_f32 v215, v215, 0x3a800000, v222
	v_rsq_f32_e32 v208, v208
	v_rsq_f32_e32 v209, v209
	v_rsq_f32_e32 v210, v210
	v_rsq_f32_e32 v211, v211
	v_rsq_f32_e32 v212, v212
	v_rsq_f32_e32 v213, v213
	v_rsq_f32_e32 v214, v214
	v_rsq_f32_e32 v215, v215
	s_ashr_i32 s21, s19, 11
	s_mul_hi_i32 s39, s21, 0x1414000
	s_mul_i32 s21, s21, 0x1414000
	v_bitop3_b32 v149, s19, v230, v97 bitop3:0xc8
	s_add_u32 s38, s4, s21
	s_addc_u32 s39, s5, s39
	v_mul_u32_u24_e32 v0, 0xb00, v149
	v_lshlrev_b32_e32 v0, 1, v0
	v_lshl_add_u32 v220, v184, 1, v0
	v_mul_f32_e32 v232, v208, v208
	v_mul_f32_e32 v233, 0xbfb8aa3b, v208
	v_mul_f32_e32 v234, v209, v209
	v_mul_f32_e32 v235, 0xbfb8aa3b, v209
	v_mul_f32_e32 v236, v210, v210
	v_mul_f32_e32 v237, 0xbfb8aa3b, v210
	v_mul_f32_e32 v238, v211, v211
	v_mul_f32_e32 v239, 0xbfb8aa3b, v211
	v_mul_f32_e32 v240, v212, v212
	v_mul_f32_e32 v241, 0xbfb8aa3b, v212
	v_mul_f32_e32 v242, v213, v213
	v_mul_f32_e32 v243, 0xbfb8aa3b, v213
	v_mul_f32_e32 v244, v214, v214
	v_mul_f32_e32 v245, 0xbfb8aa3b, v214
	v_mul_f32_e32 v246, v215, v215
	v_mul_f32_e32 v247, 0xbfb8aa3b, v215
	v_pk_mul_f32 v[208:209], v[130:131], v[232:233] op_sel:[0,1] op_sel_hi:[1,1]
	v_pk_mul_f32 v[210:211], v[132:133], v[232:233] op_sel:[0,1] op_sel_hi:[1,1]
	v_pk_mul_f32 v[212:213], v[126:127], v[232:233] op_sel:[0,1] op_sel_hi:[1,1]
	v_pk_mul_f32 v[214:215], v[128:129], v[232:233] op_sel:[0,1] op_sel_hi:[1,1]
	v_exp_f32_e32 v208, v208
	v_exp_f32_e32 v209, v209
	v_exp_f32_e32 v210, v210
	v_exp_f32_e32 v211, v211
	v_exp_f32_e32 v212, v212
	v_exp_f32_e32 v213, v213
	v_exp_f32_e32 v214, v214
	v_exp_f32_e32 v215, v215
	v_pk_add_f32 v[208:209], v[208:209], 1.0 op_sel_hi:[1,0]
	v_pk_add_f32 v[210:211], v[210:211], 1.0 op_sel_hi:[1,0]
	v_pk_add_f32 v[212:213], v[212:213], 1.0 op_sel_hi:[1,0]
	v_pk_add_f32 v[214:215], v[214:215], 1.0 op_sel_hi:[1,0]
	v_rcp_f32_e32 v208, v208
	v_rcp_f32_e32 v209, v209
	v_rcp_f32_e32 v210, v210
	v_rcp_f32_e32 v211, v211
	v_rcp_f32_e32 v212, v212
	v_rcp_f32_e32 v213, v213
	v_rcp_f32_e32 v214, v214
	v_rcp_f32_e32 v215, v215
	v_pk_mul_f32 v[130:131], v[130:131], v[122:123]
	v_pk_mul_f32 v[132:133], v[132:133], v[124:125]
	v_pk_mul_f32 v[126:127], v[126:127], v[118:119]
	v_pk_mul_f32 v[128:129], v[128:129], v[120:121]
	v_pk_mul_f32 v[208:209], v[208:209], v[232:233] op_sel_hi:[1,0]
	v_pk_mul_f32 v[210:211], v[210:211], v[232:233] op_sel_hi:[1,0]
	v_pk_mul_f32 v[212:213], v[212:213], v[232:233] op_sel_hi:[1,0]
	v_pk_mul_f32 v[214:215], v[214:215], v[232:233] op_sel_hi:[1,0]
	v_pk_mul_f32 v[130:131], v[130:131], v[208:209]
	v_pk_mul_f32 v[132:133], v[132:133], v[210:211]
	v_pk_mul_f32 v[126:127], v[126:127], v[212:213]
	v_pk_mul_f32 v[128:129], v[128:129], v[214:215]
	v_cvt_pk_bf16_f32 v216, v130, v131
	v_cvt_pk_bf16_f32 v217, v132, v133
	v_cvt_pk_bf16_f32 v218, v126, v127
	v_cvt_pk_bf16_f32 v219, v128, v129
	global_store_dwordx4 v220, v[216:219], s[38:39]
	v_pk_mul_f32 v[208:209], v[114:115], v[234:235] op_sel:[0,1] op_sel_hi:[1,1]
	v_pk_mul_f32 v[210:211], v[116:117], v[234:235] op_sel:[0,1] op_sel_hi:[1,1]
	v_pk_mul_f32 v[212:213], v[110:111], v[234:235] op_sel:[0,1] op_sel_hi:[1,1]
	v_pk_mul_f32 v[214:215], v[112:113], v[234:235] op_sel:[0,1] op_sel_hi:[1,1]
	v_exp_f32_e32 v208, v208
	v_exp_f32_e32 v209, v209
	v_exp_f32_e32 v210, v210
	v_exp_f32_e32 v211, v211
	v_exp_f32_e32 v212, v212
	v_exp_f32_e32 v213, v213
	v_exp_f32_e32 v214, v214
	v_exp_f32_e32 v215, v215
	v_pk_add_f32 v[208:209], v[208:209], 1.0 op_sel_hi:[1,0]
	v_pk_add_f32 v[210:211], v[210:211], 1.0 op_sel_hi:[1,0]
	v_pk_add_f32 v[212:213], v[212:213], 1.0 op_sel_hi:[1,0]
	v_pk_add_f32 v[214:215], v[214:215], 1.0 op_sel_hi:[1,0]
	v_rcp_f32_e32 v208, v208
	v_rcp_f32_e32 v209, v209
	v_rcp_f32_e32 v210, v210
	v_rcp_f32_e32 v211, v211
	v_rcp_f32_e32 v212, v212
	v_rcp_f32_e32 v213, v213
	v_rcp_f32_e32 v214, v214
	v_rcp_f32_e32 v215, v215
	v_pk_mul_f32 v[114:115], v[114:115], v[106:107]
	v_pk_mul_f32 v[116:117], v[116:117], v[108:109]
	v_pk_mul_f32 v[110:111], v[110:111], v[102:103]
	v_pk_mul_f32 v[112:113], v[112:113], v[104:105]
	v_pk_mul_f32 v[208:209], v[208:209], v[234:235] op_sel_hi:[1,0]
	v_pk_mul_f32 v[210:211], v[210:211], v[234:235] op_sel_hi:[1,0]
	v_pk_mul_f32 v[212:213], v[212:213], v[234:235] op_sel_hi:[1,0]
	v_pk_mul_f32 v[214:215], v[214:215], v[234:235] op_sel_hi:[1,0]
	v_pk_mul_f32 v[114:115], v[114:115], v[208:209]
	v_pk_mul_f32 v[116:117], v[116:117], v[210:211]
	v_pk_mul_f32 v[110:111], v[110:111], v[212:213]
	v_pk_mul_f32 v[112:113], v[112:113], v[214:215]
	v_cvt_pk_bf16_f32 v248, v114, v115
	v_cvt_pk_bf16_f32 v249, v116, v117
	v_cvt_pk_bf16_f32 v250, v110, v111
	v_cvt_pk_bf16_f32 v251, v112, v113
	v_add_u32_e32 v221, 0x16000, v220
	global_store_dwordx4 v221, v[248:251], s[38:39]
	v_pk_mul_f32 v[208:209], v[98:99], v[236:237] op_sel:[0,1] op_sel_hi:[1,1]
	v_pk_mul_f32 v[210:211], v[100:101], v[236:237] op_sel:[0,1] op_sel_hi:[1,1]
	v_pk_mul_f32 v[212:213], v[90:91], v[236:237] op_sel:[0,1] op_sel_hi:[1,1]
	v_pk_mul_f32 v[214:215], v[92:93], v[236:237] op_sel:[0,1] op_sel_hi:[1,1]
	v_exp_f32_e32 v208, v208
	v_exp_f32_e32 v209, v209
	v_exp_f32_e32 v210, v210
	v_exp_f32_e32 v211, v211
	v_exp_f32_e32 v212, v212
	v_exp_f32_e32 v213, v213
	v_exp_f32_e32 v214, v214
	v_exp_f32_e32 v215, v215
	v_pk_add_f32 v[208:209], v[208:209], 1.0 op_sel_hi:[1,0]
	v_pk_add_f32 v[210:211], v[210:211], 1.0 op_sel_hi:[1,0]
	v_pk_add_f32 v[212:213], v[212:213], 1.0 op_sel_hi:[1,0]
	v_pk_add_f32 v[214:215], v[214:215], 1.0 op_sel_hi:[1,0]
	v_rcp_f32_e32 v208, v208
	v_rcp_f32_e32 v209, v209
	v_rcp_f32_e32 v210, v210
	v_rcp_f32_e32 v211, v211
	v_rcp_f32_e32 v212, v212
	v_rcp_f32_e32 v213, v213
	v_rcp_f32_e32 v214, v214
	v_rcp_f32_e32 v215, v215
	v_pk_mul_f32 v[98:99], v[98:99], v[86:87]
	v_pk_mul_f32 v[100:101], v[100:101], v[88:89]
	v_pk_mul_f32 v[90:91], v[90:91], v[82:83]
	v_pk_mul_f32 v[92:93], v[92:93], v[84:85]
	v_pk_mul_f32 v[208:209], v[208:209], v[236:237] op_sel_hi:[1,0]
	v_pk_mul_f32 v[210:211], v[210:211], v[236:237] op_sel_hi:[1,0]
	v_pk_mul_f32 v[212:213], v[212:213], v[236:237] op_sel_hi:[1,0]
	v_pk_mul_f32 v[214:215], v[214:215], v[236:237] op_sel_hi:[1,0]
	v_pk_mul_f32 v[98:99], v[98:99], v[208:209]
	v_pk_mul_f32 v[100:101], v[100:101], v[210:211]
	v_pk_mul_f32 v[90:91], v[90:91], v[212:213]
	v_pk_mul_f32 v[92:93], v[92:93], v[214:215]
	v_cvt_pk_bf16_f32 v216, v98, v99
	v_cvt_pk_bf16_f32 v217, v100, v101
	v_cvt_pk_bf16_f32 v218, v90, v91
	v_cvt_pk_bf16_f32 v219, v92, v93
	v_add_u32_e32 v221, 0x2c000, v220
	global_store_dwordx4 v221, v[216:219], s[38:39]
	v_pk_mul_f32 v[208:209], v[78:79], v[238:239] op_sel:[0,1] op_sel_hi:[1,1]
	v_pk_mul_f32 v[210:211], v[80:81], v[238:239] op_sel:[0,1] op_sel_hi:[1,1]
	v_pk_mul_f32 v[212:213], v[74:75], v[238:239] op_sel:[0,1] op_sel_hi:[1,1]
	v_pk_mul_f32 v[214:215], v[76:77], v[238:239] op_sel:[0,1] op_sel_hi:[1,1]
	v_exp_f32_e32 v208, v208
	v_exp_f32_e32 v209, v209
	v_exp_f32_e32 v210, v210
	v_exp_f32_e32 v211, v211
	v_exp_f32_e32 v212, v212
	v_exp_f32_e32 v213, v213
	v_exp_f32_e32 v214, v214
	v_exp_f32_e32 v215, v215
	v_pk_add_f32 v[208:209], v[208:209], 1.0 op_sel_hi:[1,0]
	v_pk_add_f32 v[210:211], v[210:211], 1.0 op_sel_hi:[1,0]
	v_pk_add_f32 v[212:213], v[212:213], 1.0 op_sel_hi:[1,0]
	v_pk_add_f32 v[214:215], v[214:215], 1.0 op_sel_hi:[1,0]
	v_rcp_f32_e32 v208, v208
	v_rcp_f32_e32 v209, v209
	v_rcp_f32_e32 v210, v210
	v_rcp_f32_e32 v211, v211
	v_rcp_f32_e32 v212, v212
	v_rcp_f32_e32 v213, v213
	v_rcp_f32_e32 v214, v214
	v_rcp_f32_e32 v215, v215
	v_pk_mul_f32 v[78:79], v[78:79], v[70:71]
	v_pk_mul_f32 v[80:81], v[80:81], v[72:73]
	v_pk_mul_f32 v[74:75], v[74:75], v[66:67]
	v_pk_mul_f32 v[76:77], v[76:77], v[68:69]
	v_pk_mul_f32 v[208:209], v[208:209], v[238:239] op_sel_hi:[1,0]
	v_pk_mul_f32 v[210:211], v[210:211], v[238:239] op_sel_hi:[1,0]
	v_pk_mul_f32 v[212:213], v[212:213], v[238:239] op_sel_hi:[1,0]
	v_pk_mul_f32 v[214:215], v[214:215], v[238:239] op_sel_hi:[1,0]
	v_pk_mul_f32 v[78:79], v[78:79], v[208:209]
	v_pk_mul_f32 v[80:81], v[80:81], v[210:211]
	v_pk_mul_f32 v[74:75], v[74:75], v[212:213]
	v_pk_mul_f32 v[76:77], v[76:77], v[214:215]
	v_cvt_pk_bf16_f32 v248, v78, v79
	v_cvt_pk_bf16_f32 v249, v80, v81
	v_cvt_pk_bf16_f32 v250, v74, v75
	v_cvt_pk_bf16_f32 v251, v76, v77
	v_add_u32_e32 v221, 0x42000, v220
	global_store_dwordx4 v221, v[248:251], s[38:39]
	v_pk_mul_f32 v[208:209], v[62:63], v[240:241] op_sel:[0,1] op_sel_hi:[1,1]
	v_pk_mul_f32 v[210:211], v[64:65], v[240:241] op_sel:[0,1] op_sel_hi:[1,1]
	v_pk_mul_f32 v[212:213], v[58:59], v[240:241] op_sel:[0,1] op_sel_hi:[1,1]
	v_pk_mul_f32 v[214:215], v[60:61], v[240:241] op_sel:[0,1] op_sel_hi:[1,1]
	v_exp_f32_e32 v208, v208
	v_exp_f32_e32 v209, v209
	v_exp_f32_e32 v210, v210
	v_exp_f32_e32 v211, v211
	v_exp_f32_e32 v212, v212
	v_exp_f32_e32 v213, v213
	v_exp_f32_e32 v214, v214
	v_exp_f32_e32 v215, v215
	v_pk_add_f32 v[208:209], v[208:209], 1.0 op_sel_hi:[1,0]
	v_pk_add_f32 v[210:211], v[210:211], 1.0 op_sel_hi:[1,0]
	v_pk_add_f32 v[212:213], v[212:213], 1.0 op_sel_hi:[1,0]
	v_pk_add_f32 v[214:215], v[214:215], 1.0 op_sel_hi:[1,0]
	v_rcp_f32_e32 v208, v208
	v_rcp_f32_e32 v209, v209
	v_rcp_f32_e32 v210, v210
	v_rcp_f32_e32 v211, v211
	v_rcp_f32_e32 v212, v212
	v_rcp_f32_e32 v213, v213
	v_rcp_f32_e32 v214, v214
	v_rcp_f32_e32 v215, v215
	v_pk_mul_f32 v[62:63], v[62:63], v[54:55]
	v_pk_mul_f32 v[64:65], v[64:65], v[56:57]
	v_pk_mul_f32 v[58:59], v[58:59], v[50:51]
	v_pk_mul_f32 v[60:61], v[60:61], v[52:53]
	v_pk_mul_f32 v[208:209], v[208:209], v[240:241] op_sel_hi:[1,0]
	v_pk_mul_f32 v[210:211], v[210:211], v[240:241] op_sel_hi:[1,0]
	v_pk_mul_f32 v[212:213], v[212:213], v[240:241] op_sel_hi:[1,0]
	v_pk_mul_f32 v[214:215], v[214:215], v[240:241] op_sel_hi:[1,0]
	v_pk_mul_f32 v[62:63], v[62:63], v[208:209]
	v_pk_mul_f32 v[64:65], v[64:65], v[210:211]
	v_pk_mul_f32 v[58:59], v[58:59], v[212:213]
	v_pk_mul_f32 v[60:61], v[60:61], v[214:215]
	v_cvt_pk_bf16_f32 v216, v62, v63
	v_cvt_pk_bf16_f32 v217, v64, v65
	v_cvt_pk_bf16_f32 v218, v58, v59
	v_cvt_pk_bf16_f32 v219, v60, v61
	v_add_u32_e32 v221, 0xb0000, v220
	global_store_dwordx4 v221, v[216:219], s[38:39]
	v_pk_mul_f32 v[208:209], v[46:47], v[242:243] op_sel:[0,1] op_sel_hi:[1,1]
	v_pk_mul_f32 v[210:211], v[48:49], v[242:243] op_sel:[0,1] op_sel_hi:[1,1]
	v_pk_mul_f32 v[212:213], v[42:43], v[242:243] op_sel:[0,1] op_sel_hi:[1,1]
	v_pk_mul_f32 v[214:215], v[44:45], v[242:243] op_sel:[0,1] op_sel_hi:[1,1]
	v_exp_f32_e32 v208, v208
	v_exp_f32_e32 v209, v209
	v_exp_f32_e32 v210, v210
	v_exp_f32_e32 v211, v211
	v_exp_f32_e32 v212, v212
	v_exp_f32_e32 v213, v213
	v_exp_f32_e32 v214, v214
	v_exp_f32_e32 v215, v215
	v_pk_add_f32 v[208:209], v[208:209], 1.0 op_sel_hi:[1,0]
	v_pk_add_f32 v[210:211], v[210:211], 1.0 op_sel_hi:[1,0]
	v_pk_add_f32 v[212:213], v[212:213], 1.0 op_sel_hi:[1,0]
	v_pk_add_f32 v[214:215], v[214:215], 1.0 op_sel_hi:[1,0]
	v_rcp_f32_e32 v208, v208
	v_rcp_f32_e32 v209, v209
	v_rcp_f32_e32 v210, v210
	v_rcp_f32_e32 v211, v211
	v_rcp_f32_e32 v212, v212
	v_rcp_f32_e32 v213, v213
	v_rcp_f32_e32 v214, v214
	v_rcp_f32_e32 v215, v215
	v_pk_mul_f32 v[46:47], v[46:47], v[38:39]
	v_pk_mul_f32 v[48:49], v[48:49], v[40:41]
	v_pk_mul_f32 v[42:43], v[42:43], v[34:35]
	v_pk_mul_f32 v[44:45], v[44:45], v[36:37]
	v_pk_mul_f32 v[208:209], v[208:209], v[242:243] op_sel_hi:[1,0]
	v_pk_mul_f32 v[210:211], v[210:211], v[242:243] op_sel_hi:[1,0]
	v_pk_mul_f32 v[212:213], v[212:213], v[242:243] op_sel_hi:[1,0]
	v_pk_mul_f32 v[214:215], v[214:215], v[242:243] op_sel_hi:[1,0]
	v_pk_mul_f32 v[46:47], v[46:47], v[208:209]
	v_pk_mul_f32 v[48:49], v[48:49], v[210:211]
	v_pk_mul_f32 v[42:43], v[42:43], v[212:213]
	v_pk_mul_f32 v[44:45], v[44:45], v[214:215]
	v_cvt_pk_bf16_f32 v248, v46, v47
	v_cvt_pk_bf16_f32 v249, v48, v49
	v_cvt_pk_bf16_f32 v250, v42, v43
	v_cvt_pk_bf16_f32 v251, v44, v45
	v_add_u32_e32 v221, 0xc6000, v220
	global_store_dwordx4 v221, v[248:251], s[38:39]
	v_pk_mul_f32 v[208:209], v[30:31], v[244:245] op_sel:[0,1] op_sel_hi:[1,1]
	v_pk_mul_f32 v[210:211], v[32:33], v[244:245] op_sel:[0,1] op_sel_hi:[1,1]
	v_pk_mul_f32 v[212:213], v[26:27], v[244:245] op_sel:[0,1] op_sel_hi:[1,1]
	v_pk_mul_f32 v[214:215], v[28:29], v[244:245] op_sel:[0,1] op_sel_hi:[1,1]
	v_exp_f32_e32 v208, v208
	v_exp_f32_e32 v209, v209
	v_exp_f32_e32 v210, v210
	v_exp_f32_e32 v211, v211
	v_exp_f32_e32 v212, v212
	v_exp_f32_e32 v213, v213
	v_exp_f32_e32 v214, v214
	v_exp_f32_e32 v215, v215
	v_pk_add_f32 v[208:209], v[208:209], 1.0 op_sel_hi:[1,0]
	v_pk_add_f32 v[210:211], v[210:211], 1.0 op_sel_hi:[1,0]
	v_pk_add_f32 v[212:213], v[212:213], 1.0 op_sel_hi:[1,0]
	v_pk_add_f32 v[214:215], v[214:215], 1.0 op_sel_hi:[1,0]
	v_rcp_f32_e32 v208, v208
	v_rcp_f32_e32 v209, v209
	v_rcp_f32_e32 v210, v210
	v_rcp_f32_e32 v211, v211
	v_rcp_f32_e32 v212, v212
	v_rcp_f32_e32 v213, v213
	v_rcp_f32_e32 v214, v214
	v_rcp_f32_e32 v215, v215
	v_pk_mul_f32 v[30:31], v[30:31], v[22:23]
	v_pk_mul_f32 v[32:33], v[32:33], v[24:25]
	v_pk_mul_f32 v[26:27], v[26:27], v[18:19]
	v_pk_mul_f32 v[28:29], v[28:29], v[20:21]
	v_pk_mul_f32 v[208:209], v[208:209], v[244:245] op_sel_hi:[1,0]
	v_pk_mul_f32 v[210:211], v[210:211], v[244:245] op_sel_hi:[1,0]
	v_pk_mul_f32 v[212:213], v[212:213], v[244:245] op_sel_hi:[1,0]
	v_pk_mul_f32 v[214:215], v[214:215], v[244:245] op_sel_hi:[1,0]
	v_pk_mul_f32 v[30:31], v[30:31], v[208:209]
	v_pk_mul_f32 v[32:33], v[32:33], v[210:211]
	v_pk_mul_f32 v[26:27], v[26:27], v[212:213]
	v_pk_mul_f32 v[28:29], v[28:29], v[214:215]
	v_cvt_pk_bf16_f32 v216, v30, v31
	v_cvt_pk_bf16_f32 v217, v32, v33
	v_cvt_pk_bf16_f32 v218, v26, v27
	v_cvt_pk_bf16_f32 v219, v28, v29
	v_add_u32_e32 v221, 0xdc000, v220
	global_store_dwordx4 v221, v[216:219], s[38:39]
	v_pk_mul_f32 v[208:209], v[14:15], v[246:247] op_sel:[0,1] op_sel_hi:[1,1]
	v_pk_mul_f32 v[210:211], v[16:17], v[246:247] op_sel:[0,1] op_sel_hi:[1,1]
	v_pk_mul_f32 v[212:213], v[10:11], v[246:247] op_sel:[0,1] op_sel_hi:[1,1]
	v_pk_mul_f32 v[214:215], v[12:13], v[246:247] op_sel:[0,1] op_sel_hi:[1,1]
	v_exp_f32_e32 v208, v208
	v_exp_f32_e32 v209, v209
	v_exp_f32_e32 v210, v210
	v_exp_f32_e32 v211, v211
	v_exp_f32_e32 v212, v212
	v_exp_f32_e32 v213, v213
	v_exp_f32_e32 v214, v214
	v_exp_f32_e32 v215, v215
	v_pk_add_f32 v[208:209], v[208:209], 1.0 op_sel_hi:[1,0]
	v_pk_add_f32 v[210:211], v[210:211], 1.0 op_sel_hi:[1,0]
	v_pk_add_f32 v[212:213], v[212:213], 1.0 op_sel_hi:[1,0]
	v_pk_add_f32 v[214:215], v[214:215], 1.0 op_sel_hi:[1,0]
	v_rcp_f32_e32 v208, v208
	v_rcp_f32_e32 v209, v209
	v_rcp_f32_e32 v210, v210
	v_rcp_f32_e32 v211, v211
	v_rcp_f32_e32 v212, v212
	v_rcp_f32_e32 v213, v213
	v_rcp_f32_e32 v214, v214
	v_rcp_f32_e32 v215, v215
	v_pk_mul_f32 v[14:15], v[14:15], v[6:7]
	v_pk_mul_f32 v[16:17], v[16:17], v[8:9]
	v_pk_mul_f32 v[10:11], v[10:11], v[2:3]
	v_pk_mul_f32 v[12:13], v[12:13], v[4:5]
	v_pk_mul_f32 v[208:209], v[208:209], v[246:247] op_sel_hi:[1,0]
	v_pk_mul_f32 v[210:211], v[210:211], v[246:247] op_sel_hi:[1,0]
	v_pk_mul_f32 v[212:213], v[212:213], v[246:247] op_sel_hi:[1,0]
	v_pk_mul_f32 v[214:215], v[214:215], v[246:247] op_sel_hi:[1,0]
	v_pk_mul_f32 v[14:15], v[14:15], v[208:209]
	v_pk_mul_f32 v[16:17], v[16:17], v[210:211]
	v_pk_mul_f32 v[10:11], v[10:11], v[212:213]
	v_pk_mul_f32 v[12:13], v[12:13], v[214:215]
	v_cvt_pk_bf16_f32 v248, v14, v15
	v_cvt_pk_bf16_f32 v249, v16, v17
	v_cvt_pk_bf16_f32 v250, v10, v11
	v_cvt_pk_bf16_f32 v251, v12, v13
	v_add_u32_e32 v221, 0xf2000, v220
	global_store_dwordx4 v221, v[248:251], s[38:39]
	s_mov_b32 s21, 0x16000
	s_mov_b32 s40, 0x2c000
	s_mov_b32 s19, 0x1414000
	s_andn2_b64 vcc, exec, s[36:37]
	s_mov_b64 s[36:37], -1
	s_cbranch_vccnz .LBB0_561
	s_andn2_b64 vcc, exec, s[0:1]
	s_cbranch_vccnz .LBB0_560
	s_barrier
	s_branch .LBB0_560
